# neighbourhood attention: waves 4-7 defer each key row's P.V MFMAs to the start of the next row step, so SIMD partner waves alternate MFMA-heavy and VALU-heavy blocks
# baseline (speedup 1.0000x reference)
.LBB0_231:
	s_ashr_i32 s10, s83, 8
	s_lshl_b32 s8, s10, 6
	s_bfe_u32 s3, s33, 0x40002
	s_ashr_i32 s9, s8, 31
	s_lshl_b32 s6, s3, 2
	s_bfe_u32 s85, s83, 0x40004
	s_lshl_b64 s[8:9], s[8:9], 2
	s_add_u32 s7, s4, s8
	s_addc_u32 s9, s5, s9
	s_lshl_b32 s8, s85, 3
	s_add_u32 s8, s7, s8
	s_addc_u32 s9, s9, 0
	s_add_u32 s74, s8, 0x1080
	s_addc_u32 s75, s9, 0
	s_lshl_b32 s7, s83, 2
	global_load_dword v0, v212, s[8:9] offset:128 sc1
	global_load_dword v2, v231, s[74:75] offset:4 sc1
	s_and_b32 s9, s7, 60
	v_sub_u32_e64 v1, s9, 1 clamp
	v_readlane_b32 s7, v254, 21
	v_readfirstlane_b32 s11, v1
	s_add_i32 s8, s9, s7
	s_max_u32 s7, s9, 4
	s_min_u32 s11, s11, 56
	s_sub_i32 s7, s11, s7
	s_ashr_i32 s11, s10, 31
	s_lshl_b64 s[74:75], s[10:11], 12
	s_lshl_b64 s[10:11], s[10:11], 23
	v_readlane_b32 s12, v252, 10
	s_add_u32 s76, s12, s10
	v_readlane_b32 s12, v252, 11
	s_addc_u32 s77, s12, s11
	s_lshl_b32 s78, s8, 6
	s_add_u32 s74, s74, s78
	s_addc_u32 s75, s75, 0
	v_mov_b32_e32 v149, s75
	v_or_b32_e32 v148, s74, v140
	v_readlane_b32 s74, v255, 12
	s_lshl_b32 s0, s85, 7
	s_add_i32 s95, s7, 11
	v_lshlrev_b64 v[4:5], 11, v[148:149]
	v_readlane_b32 s75, v255, 13
	v_sub_u32_e64 v65, s9, 4 clamp
	s_add_u32 s9, s87, s10
	v_readlane_b32 s10, v252, 9
	v_lshl_add_u64 v[4:5], s[74:75], 0, v[4:5]
	s_addc_u32 s11, s10, s11
	v_lshl_add_u64 v[4:5], v[4:5], 0, s[0:1]
	v_lshlrev_b32_e32 v230, 1, v142
	s_add_u32 s10, s9, s0
	v_lshl_add_u64 v[4:5], v[4:5], 0, v[230:231]
	s_addc_u32 s11, s11, 0
	s_barrier
	global_load_dwordx4 v[98:101], v[4:5], off
	v_lshl_add_u64 v[6:7], v[4:5], 0, 32
	s_mov_b64 s[74:75], 0x60
	s_add_u32 s9, s76, s0
	v_mov_b32_e32 v147, v231
	global_load_dwordx4 v[102:105], v[6:7], off
	v_lshl_add_u64 v[6:7], v[4:5], 0, 64
	v_lshl_add_u64 v[4:5], v[4:5], 0, s[74:75]
	s_addc_u32 s74, s77, 0
	v_lshl_add_u64 v[150:151], s[10:11], 0, v[146:147]
	v_readlane_b32 s10, v254, 61
	s_add_u32 s10, s9, s10
	s_addc_u32 s11, s74, 0
	s_min_i32 s9, s95, 0
	v_add_u32_e32 v1, s9, v65
	global_load_dwordx4 v[106:109], v[6:7], off
	v_lshlrev_b32_e32 v1, 6, v1
	global_load_dwordx4 v[110:113], v[4:5], off
	v_add_u32_e32 v4, v1, v141
	v_ashrrev_i32_e32 v5, 31, v4
	v_or_b32_e32 v6, v1, v145
	v_lshlrev_b32_e32 v230, 1, v144
	v_lshlrev_b64 v[4:5], 11, v[4:5]
	v_ashrrev_i32_e32 v7, 31, v6
	v_lshl_add_u64 v[152:153], s[10:11], 0, v[230:231]
	v_lshl_add_u64 v[4:5], v[150:151], 0, v[4:5]
	v_lshlrev_b64 v[6:7], 11, v[6:7]
	v_readlane_b32 s10, v252, 26
	s_mov_b32 s9, m0
	s_mov_b32 m0, s10
	s_nop 0
	global_load_lds_dwordx4 v[4:5], off
	s_mov_b32 m0, s9
	v_lshl_add_u64 v[6:7], v[152:153], 0, v[6:7]
	v_readlane_b32 s10, v252, 19
	s_mov_b32 s9, m0
	s_mov_b32 m0, s10
	s_nop 0
	global_load_lds_dwordx4 v[6:7], off
	s_mov_b32 m0, s9
	s_min_i32 s9, s95, 1
	v_add_u32_e32 v1, s9, v65
	v_lshlrev_b32_e32 v1, 6, v1
	v_add_u32_e32 v4, v1, v141
	v_ashrrev_i32_e32 v5, 31, v4
	v_or_b32_e32 v6, v1, v145
	v_lshlrev_b64 v[4:5], 11, v[4:5]
	v_ashrrev_i32_e32 v7, 31, v6
	v_lshl_add_u64 v[4:5], v[150:151], 0, v[4:5]
	v_lshlrev_b64 v[6:7], 11, v[6:7]
	v_readlane_b32 s10, v252, 20
	s_mov_b32 s9, m0
	s_mov_b32 m0, s10
	s_nop 0
	global_load_lds_dwordx4 v[4:5], off
	s_mov_b32 m0, s9
	v_lshl_add_u64 v[6:7], v[152:153], 0, v[6:7]
	v_readlane_b32 s10, v252, 21
	s_mov_b32 s9, m0
	s_mov_b32 m0, s10
	s_nop 0
	global_load_lds_dwordx4 v[6:7], off
	s_mov_b32 m0, s9
	s_min_i32 s9, s95, 2
	v_add_u32_e32 v1, s9, v65
	v_lshlrev_b32_e32 v1, 6, v1
	v_add_u32_e32 v4, v1, v141
	v_ashrrev_i32_e32 v5, 31, v4
	v_or_b32_e32 v6, v1, v145
	v_lshlrev_b64 v[4:5], 11, v[4:5]
	v_ashrrev_i32_e32 v7, 31, v6
	v_lshl_add_u64 v[4:5], v[150:151], 0, v[4:5]
	v_lshlrev_b64 v[6:7], 11, v[6:7]
	v_readlane_b32 s10, v252, 22
	s_mov_b32 s9, m0
	s_mov_b32 m0, s10
	s_nop 0
	global_load_lds_dwordx4 v[4:5], off
	s_mov_b32 m0, s9
	v_lshl_add_u64 v[6:7], v[152:153], 0, v[6:7]
	v_readlane_b32 s10, v252, 23
	s_mov_b32 s9, m0
	s_mov_b32 m0, s10
	s_nop 0
	global_load_lds_dwordx4 v[6:7], off
	s_mov_b32 m0, s9
	s_min_i32 s9, s95, 3
	v_add_u32_e32 v1, s9, v65
	v_lshlrev_b32_e32 v1, 6, v1
	v_add_u32_e32 v4, v1, v141
	v_ashrrev_i32_e32 v5, 31, v4
	v_or_b32_e32 v6, v1, v145
	v_lshlrev_b64 v[4:5], 11, v[4:5]
	v_ashrrev_i32_e32 v7, 31, v6
	v_lshl_add_u64 v[4:5], v[150:151], 0, v[4:5]
	v_lshlrev_b64 v[6:7], 11, v[6:7]
	v_readlane_b32 s10, v252, 24
	s_mov_b32 s9, m0
	s_mov_b32 m0, s10
	s_nop 0
	global_load_lds_dwordx4 v[4:5], off
	s_mov_b32 m0, s9
	v_lshl_add_u64 v[6:7], v[152:153], 0, v[6:7]
	v_readlane_b32 s10, v252, 25
	s_mov_b32 s9, m0
	s_mov_b32 m0, s10
	s_nop 0
	global_load_lds_dwordx4 v[6:7], off
	s_mov_b32 m0, s9
	s_min_i32 s9, s95, 4
	v_add_u32_e32 v1, s9, v65
	v_lshlrev_b32_e32 v1, 6, v1
	v_add_u32_e32 v4, v1, v141
	v_ashrrev_i32_e32 v5, 31, v4
	v_or_b32_e32 v6, v1, v145
	v_lshlrev_b64 v[4:5], 11, v[4:5]
	v_ashrrev_i32_e32 v7, 31, v6
	v_lshl_add_u64 v[4:5], v[150:151], 0, v[4:5]
	v_lshlrev_b64 v[6:7], 11, v[6:7]
	v_readlane_b32 s10, v252, 48
	s_mov_b32 s9, m0
	s_mov_b32 m0, s10
	s_nop 0
	global_load_lds_dwordx4 v[4:5], off
	s_mov_b32 m0, s9
	v_lshl_add_u64 v[6:7], v[152:153], 0, v[6:7]
	v_readlane_b32 s10, v252, 27
	s_mov_b32 s9, m0
	s_mov_b32 m0, s10
	s_nop 0
	global_load_lds_dwordx4 v[6:7], off
	s_mov_b32 m0, s9
	s_waitcnt vmcnt(10)
	v_readlane_b32 s10, v252, 28
	v_and_b32_e32 v3, 0xffff0000, v98
	v_lshlrev_b32_e32 v1, 16, v98
	v_mul_f32_e32 v3, v3, v3
	v_fmac_f32_e32 v3, v1, v1
	v_lshlrev_b32_e32 v1, 16, v99
	v_fmac_f32_e32 v3, v1, v1
	v_and_b32_e32 v1, 0xffff0000, v99
	v_fmac_f32_e32 v3, v1, v1
	v_lshlrev_b32_e32 v1, 16, v100
	v_fmac_f32_e32 v3, v1, v1
	v_and_b32_e32 v1, 0xffff0000, v100
	v_fmac_f32_e32 v3, v1, v1
	v_lshlrev_b32_e32 v1, 16, v101
	v_fmac_f32_e32 v3, v1, v1
	v_and_b32_e32 v1, 0xffff0000, v101
	v_fmac_f32_e32 v3, v1, v1
	v_lshlrev_b32_e32 v1, 16, v102
	v_fmac_f32_e32 v3, v1, v1
	v_and_b32_e32 v1, 0xffff0000, v102
	v_fmac_f32_e32 v3, v1, v1
	v_lshlrev_b32_e32 v1, 16, v103
	v_fmac_f32_e32 v3, v1, v1
	v_and_b32_e32 v1, 0xffff0000, v103
	v_fmac_f32_e32 v3, v1, v1
	v_lshlrev_b32_e32 v1, 16, v104
	v_fmac_f32_e32 v3, v1, v1
	v_and_b32_e32 v1, 0xffff0000, v104
	v_fmac_f32_e32 v3, v1, v1
	v_lshlrev_b32_e32 v1, 16, v105
	v_fmac_f32_e32 v3, v1, v1
	v_and_b32_e32 v1, 0xffff0000, v105
	v_fmac_f32_e32 v3, v1, v1
	v_lshlrev_b32_e32 v1, 16, v106
	v_fmac_f32_e32 v3, v1, v1
	v_and_b32_e32 v1, 0xffff0000, v106
	v_fmac_f32_e32 v3, v1, v1
	v_lshlrev_b32_e32 v1, 16, v107
	v_fmac_f32_e32 v3, v1, v1
	v_and_b32_e32 v1, 0xffff0000, v107
	v_and_b32_e32 v5, 0xffff0000, v108
	v_lshlrev_b32_e32 v4, 16, v108
	v_fmac_f32_e32 v3, v1, v1
	v_pk_mul_f32 v[4:5], v[4:5], v[4:5]
	v_sub_u32_e64 v8, s6, 1 clamp
	v_add_f32_e32 v1, v4, v3
	v_add_f32_e32 v1, v5, v1
	v_and_b32_e32 v5, 0xffff0000, v109
	v_lshlrev_b32_e32 v4, 16, v109
	v_pk_mul_f32 v[4:5], v[4:5], v[4:5]
	v_mbcnt_lo_u32_b32 v3, -1, 0
	v_mbcnt_hi_u32_b32 v3, -1, v3
	v_readlane_b32 s11, v252, 29
	v_add_f32_e32 v1, v4, v1
	v_add_f32_e32 v1, v5, v1
	v_and_b32_e32 v5, 0xffff0000, v110
	v_lshlrev_b32_e32 v4, 16, v110
	v_pk_mul_f32 v[4:5], v[4:5], v[4:5]
	v_lshlrev_b32_e32 v3, 2, v3
	v_add_f32_e32 v1, v4, v1
	v_add_f32_e32 v1, v5, v1
	v_and_b32_e32 v5, 0xffff0000, v111
	v_lshlrev_b32_e32 v4, 16, v111
	v_pk_mul_f32 v[4:5], v[4:5], v[4:5]
	v_xor_b32_e32 v3, 0x80, v3
	v_add_f32_e32 v1, v4, v1
	v_add_f32_e32 v1, v5, v1
	v_and_b32_e32 v5, 0xffff0000, v112
	v_lshlrev_b32_e32 v4, 16, v112
	v_pk_mul_f32 v[4:5], v[4:5], v[4:5]
	s_andn2_b64 vcc, exec, s[10:11]
	v_add_f32_e32 v1, v4, v1
	v_add_f32_e32 v1, v5, v1
	v_and_b32_e32 v5, 0xffff0000, v113
	v_lshlrev_b32_e32 v4, 16, v113
	v_pk_mul_f32 v[4:5], v[4:5], v[4:5]
	v_readfirstlane_b32 s9, v8
	v_add_f32_e32 v1, v4, v1
	v_add_f32_e32 v1, v5, v1
	ds_bpermute_b32 v3, v3, v1
	s_mov_b32 s100, 0
	s_mov_b32 s101, 0
	s_cbranch_vccnz .LBB0_233
	s_setprio 1
	s_mov_b32 s100, 1

.LBB0_235:
	s_mul_hi_u32 s11, s8, 0x24924925
	s_sub_i32 s74, s8, s11
	s_lshr_b32 s74, s74, 1
	s_add_i32 s74, s74, s11
	s_lshr_b32 s11, s74, 2
	s_add_i32 s74, s6, s87
	s_add_i32 s76, s74, 8
	s_add_i32 s74, s87, 17
	s_min_i32 s74, s74, s95
	v_add_u32_e32 v66, s74, v65
	v_lshlrev_b32_e32 v68, 6, v66
	s_mul_i32 s11, s11, 0x1c000
	v_add_u32_e32 v66, v68, v141
	s_sub_i32 s11, s9, s11
	v_ashrrev_i32_e32 v67, 31, v66
	v_or_b32_e32 v68, v68, v145
	s_waitcnt vmcnt(8) lgkmcnt(0)
	s_barrier
	v_lshlrev_b64 v[66:67], 11, v[66:67]
	v_ashrrev_i32_e32 v69, 31, v68
	s_add_i32 s11, s11, 0
	v_lshl_add_u64 v[66:67], v[150:151], 0, v[66:67]
	v_lshlrev_b64 v[68:69], 11, v[68:69]
	s_add_i32 s74, s11, 0x14000
	s_mov_b32 s75, m0
	s_mov_b32 m0, s74
	s_nop 0
	global_load_lds_dwordx4 v[66:67], off
	s_mov_b32 m0, s75
	s_add_i32 s11, s11, 0x16000
	v_lshl_add_u64 v[68:69], v[152:153], 0, v[68:69]
	s_mov_b32 s74, m0
	s_mov_b32 m0, s11
	s_nop 0
	global_load_lds_dwordx4 v[68:69], off
	s_mov_b32 m0, s74
	s_cmp_eq_u32 s101, 0
	s_cbranch_scc1 .Lna_nopend
	v_readlane_b32 s76, v252, 30
	v_readlane_b32 s77, v252, 31
	s_nop 4
	v_add3_u32 v66, s99, v155, v156
	s_andn2_b64 vcc, exec, s[76:77]
	v_cndmask_b32_e64 v67, 0, 1, s[76:77]
	v_cmp_ne_u32_e64 s[74:75], 1, v67
	v_add_u32_e32 v66, v66, v144
	ds_read_b64_tr_b16 v[174:175], v66 offset:8192
	ds_read_b64_tr_b16 v[176:177], v66 offset:8704
	ds_read_b64_tr_b16 v[178:179], v66 offset:9216
	ds_read_b64_tr_b16 v[180:181], v66 offset:9728
	ds_read_b64_tr_b16 v[182:183], v66 offset:10240
	ds_read_b64_tr_b16 v[184:185], v66 offset:10752
	ds_read_b64_tr_b16 v[186:187], v66 offset:11264
	ds_read_b64_tr_b16 v[188:189], v66 offset:11776
	ds_read_b64_tr_b16 v[190:191], v66 offset:12288
	ds_read_b64_tr_b16 v[192:193], v66 offset:12800
	ds_read_b64_tr_b16 v[194:195], v66 offset:13312
	ds_read_b64_tr_b16 v[196:197], v66 offset:13824
	s_cbranch_vccnz .Lna_d242a
	s_waitcnt lgkmcnt(10)
	v_mfma_f32_32x32x16_bf16 v[16:31], v[174:177], v[114:117], v[16:31]

.Lna_d248a:
	s_waitcnt lgkmcnt(0)
	v_add_f32_e32 v64, v64, v163
	s_mov_b32 s101, 0
	s_add_i32 s74, s6, s87
	s_add_i32 s76, s74, 8
.Lna_nopend:
	s_cmp_lt_u32 s76, s81
	s_cselect_b64 s[74:75], -1, 0
	s_cmp_gt_u32 s76, s3
	s_cselect_b64 s[76:77], -1, 0
	s_or_b64 s[74:75], s[74:75], s[76:77]
	s_and_b64 vcc, exec, s[74:75]
	s_cbranch_vccnz .LBB0_249
	s_mul_hi_u32 s11, s10, 0x24924925
	s_sub_i32 s74, s10, s11
	s_lshr_b32 s74, s74, 1
	s_add_i32 s74, s74, s11
	s_lshr_b32 s11, s74, 2
	s_mul_i32 s11, s11, 0x1c000
	s_sub_i32 s11, s78, s11
	s_add_i32 s11, s11, 0
	v_add_u32_e32 v130, s11, v158
	v_add_u32_e32 v70, v130, v154
	v_add_u32_e32 v126, v130, v159
	ds_read_b128 v[174:177], v70
	ds_read_b128 v[178:181], v70 offset:4096
	v_add_u32_e32 v131, v130, v160
	ds_read_b128 v[182:185], v126
	ds_read_b128 v[186:189], v126 offset:4096
	v_add_u32_e32 v130, v130, v161
	ds_read_b128 v[190:193], v131
	ds_read_b128 v[194:197], v131 offset:4096
	ds_read_b128 v[198:201], v130
	ds_read_b128 v[202:205], v130 offset:4096
	v_readlane_b32 s76, v252, 32
	v_readlane_b32 s77, v252, 33
	v_add_u32_e32 v168, 0, v147
	s_mov_b64 s[74:75], -1
	v_add_u32_e32 v165, 0x20670, v168
	v_add_u32_e32 v164, 0x20678, v168
	v_add_u32_e32 v167, 0x20650, v168
	v_add_u32_e32 v166, 0x20658, v168
	s_and_b64 vcc, exec, s[76:77]
	s_waitcnt lgkmcnt(7)
	v_mfma_f32_32x32x16_bf16 v[82:97], v[174:177], v[98:101], v[32:47]
	s_waitcnt lgkmcnt(6)
	v_mfma_f32_32x32x16_bf16 v[66:81], v[178:181], v[98:101], v[48:63]
	s_waitcnt lgkmcnt(5)
	v_mfma_f32_32x32x16_bf16 v[82:97], v[182:185], v[102:105], v[82:97]
	s_waitcnt lgkmcnt(4)
	v_mfma_f32_32x32x16_bf16 v[66:81], v[186:189], v[102:105], v[66:81]
	s_waitcnt lgkmcnt(3)
	v_mfma_f32_32x32x16_bf16 v[82:97], v[190:193], v[106:109], v[82:97]
	s_waitcnt lgkmcnt(2)
	v_mfma_f32_32x32x16_bf16 v[66:81], v[194:197], v[106:109], v[66:81]
	s_waitcnt lgkmcnt(1)
	v_mfma_f32_32x32x16_bf16 v[82:97], v[198:201], v[110:113], v[82:97]
	s_waitcnt lgkmcnt(0)
	v_mfma_f32_32x32x16_bf16 v[66:81], v[202:205], v[110:113], v[66:81]
	s_cbranch_vccz .LBB0_238
	v_add_u32_e32 v122, 0x20690, v168
	v_add_u32_e32 v124, 0x20698, v168
	v_add_u32_e32 v126, 0x206b0, v168
	v_add_u32_e32 v128, 0x206b8, v168
	v_add_u32_e32 v132, 0x206d0, v168
	v_add_u32_e32 v136, 0x206d8, v168
	ds_read2_b32 v[122:123], v122 offset1:1
	ds_read2_b32 v[124:125], v124 offset1:1
	ds_read2_b32 v[126:127], v126 offset1:1
	ds_read2_b32 v[128:129], v128 offset1:1
	ds_read2_b32 v[130:131], v165 offset1:1
	ds_read2_b32 v[132:133], v132 offset1:1
	ds_read2_b32 v[134:135], v164 offset1:1
	ds_read2_b32 v[136:137], v136 offset1:1
	ds_read2_b32 v[170:171], v167 offset1:1
	ds_read2_b32 v[172:173], v166 offset1:1
	s_mov_b64 s[74:75], 0
	s_waitcnt lgkmcnt(1)
	v_mov_b32_e32 v163, v170
	s_waitcnt lgkmcnt(0)
	v_mov_b32_e32 v169, v172
	s_nop 0
	v_add_f32_e32 v130, v66, v130
	v_exp_f32_e32 v130, v130
	v_add_f32_e32 v131, v67, v131
	v_exp_f32_e32 v131, v131
	v_add_f32_e32 v134, v68, v134
	v_exp_f32_e32 v134, v134
	v_add_f32_e32 v135, v69, v135
	v_exp_f32_e32 v135, v135
	v_add_f32_e32 v70, v70, v122
	v_add_f32_e32 v170, 0, v130
	v_exp_f32_e32 v70, v70
	v_add_f32_e32 v71, v71, v123
	v_add_f32_e32 v170, v131, v170
	v_exp_f32_e32 v71, v71
	v_add_f32_e32 v72, v72, v124
	v_add_f32_e32 v170, v134, v170
	v_exp_f32_e32 v72, v72
	v_add_f32_e32 v73, v73, v125
	v_add_f32_e32 v170, v135, v170
	v_exp_f32_e32 v73, v73
	v_add_f32_e32 v74, v74, v126
	v_add_f32_e32 v122, v70, v170
	v_exp_f32_e32 v74, v74
	v_add_f32_e32 v75, v75, v127
	v_add_f32_e32 v122, v71, v122
	v_exp_f32_e32 v75, v75
	v_add_f32_e32 v76, v76, v128
	v_add_f32_e32 v122, v72, v122
	v_exp_f32_e32 v76, v76
	v_add_f32_e32 v77, v77, v129
	v_add_f32_e32 v122, v73, v122
	v_exp_f32_e32 v77, v77
	v_add_f32_e32 v78, v78, v132
	v_add_f32_e32 v122, v74, v122
	v_exp_f32_e32 v78, v78
	v_add_f32_e32 v79, v79, v133
	v_add_f32_e32 v122, v75, v122
	v_exp_f32_e32 v79, v79
	v_add_f32_e32 v80, v80, v136
	v_add_f32_e32 v122, v76, v122
	v_exp_f32_e32 v80, v80
	v_add_f32_e32 v81, v81, v137
	v_add_f32_e32 v122, v77, v122
	v_exp_f32_e32 v81, v81
	v_add_f32_e32 v123, v94, v163
	v_add_f32_e32 v122, v78, v122
	v_exp_f32_e32 v123, v123
	v_add_f32_e32 v124, v95, v171
	v_add_f32_e32 v122, v79, v122
	v_exp_f32_e32 v124, v124
	v_add_f32_e32 v125, v96, v169
	v_add_f32_e32 v126, v97, v173
	v_add_f32_e32 v122, v80, v122
	v_exp_f32_e32 v125, v125
	v_exp_f32_e32 v126, v126
	v_add_f32_e32 v122, v81, v122
	v_add_f32_e32 v122, v123, v122
	v_add_f32_e32 v122, v124, v122
	v_add_f32_e32 v122, v125, v122
	v_cvt_pk_bf16_f32 v132, v123, v124
	v_cvt_pk_bf16_f32 v133, v125, v126
	v_cvt_pk_bf16_f32 v124, v78, v79
	v_cvt_pk_bf16_f32 v125, v80, v81
	v_add_f32_e32 v163, v126, v122
	v_cvt_pk_bf16_f32 v127, v134, v135
	v_cvt_pk_bf16_f32 v122, v74, v75
	v_cvt_pk_bf16_f32 v123, v76, v77
	v_mov_b64_e32 v[136:137], v[124:125]
	v_cvt_pk_bf16_f32 v126, v130, v131
	v_cvt_pk_bf16_f32 v128, v70, v71
	v_cvt_pk_bf16_f32 v129, v72, v73
	v_mov_b64_e32 v[134:135], v[122:123]

.LBB0_240:
	s_cmp_eq_u32 s100, 0
	s_cbranch_scc1 .Lna_pvnow
	s_mov_b32 s101, 1
	s_mov_b32 s99, s11
	s_branch .LBB0_250

.LBB0_252:
	s_cmp_eq_u32 s101, 0
	s_cbranch_scc1 .Lna_fin
	v_readlane_b32 s76, v252, 30
	v_readlane_b32 s77, v252, 31
	s_nop 4
	v_add3_u32 v66, s99, v155, v156
	s_andn2_b64 vcc, exec, s[76:77]
	v_cndmask_b32_e64 v67, 0, 1, s[76:77]
	v_cmp_ne_u32_e64 s[74:75], 1, v67
	v_add_u32_e32 v66, v66, v144
	ds_read_b64_tr_b16 v[174:175], v66 offset:8192
	ds_read_b64_tr_b16 v[176:177], v66 offset:8704
	ds_read_b64_tr_b16 v[178:179], v66 offset:9216
	ds_read_b64_tr_b16 v[180:181], v66 offset:9728
	ds_read_b64_tr_b16 v[182:183], v66 offset:10240
	ds_read_b64_tr_b16 v[184:185], v66 offset:10752
	ds_read_b64_tr_b16 v[186:187], v66 offset:11264
	ds_read_b64_tr_b16 v[188:189], v66 offset:11776
	ds_read_b64_tr_b16 v[190:191], v66 offset:12288
	ds_read_b64_tr_b16 v[192:193], v66 offset:12800
	ds_read_b64_tr_b16 v[194:195], v66 offset:13312
	ds_read_b64_tr_b16 v[196:197], v66 offset:13824
	s_cbranch_vccnz .Lna_d242b
	s_waitcnt lgkmcnt(10)
	v_mfma_f32_32x32x16_bf16 v[16:31], v[174:177], v[114:117], v[16:31]

.Lna_d248b:
	s_waitcnt lgkmcnt(0)
	v_add_f32_e32 v64, v64, v163
	s_mov_b32 s101, 0
	s_nop 7
	s_nop 7
	s_nop 7
